# FFN-in GEMM epilogue: drain of the next tile's prefetched slabs moved from the epilogue start to its end (counted wait behind the 8 stores), on top of the pipelined row-stat loads
# speedup vs baseline: 1.0048x; 1.0012x over previous
; __device__ __forceinline__ u32x4 pack8(const f32x4 a, const f32x4 b) { u32x4 w; w.x = cvt_pk_bf16(a[0], a[1]); w.y = cvt_pk_bf16(a[2], a[3]); w.z = cvt_pk_bf16(b[0], b[1]); w.w = cvt_pk_bf16(b[2], b[3]); return w; }
; __device__ __forceinline__ void rows_rstd8(const float* pss, int row0, int fq, float (&rs)[2][4]) {
;     float p[8], q[8];
; #pragma unroll
;     for (int k = 0; k < 8; ++k) p[k] = pss[(size_t)fq * PSS_M + row0 + (k >> 2) * HALF + (k & 3) * 16];
;     asm volatile("" : "+v"(p[0]), "+v"(p[1]), "+v"(p[2]), "+v"(p[3]), "+v"(p[4]), "+v"(p[5]), "+v"(p[6]), "+v"(p[7]));
; #pragma unroll
;     for (int k = 0; k < 8; ++k) q[k] = __shfl_xor(p[k], 16);
;     asm volatile("" : "+v"(q[0]), "+v"(q[1]), "+v"(q[2]), "+v"(q[3]), "+v"(q[4]), "+v"(q[5]), "+v"(q[6]), "+v"(q[7]));
; #pragma unroll
;     for (int k = 0; k < 8; ++k) p[k] += q[k];
; #pragma unroll
;     for (int k = 0; k < 8; ++k) q[k] = __shfl_xor(p[k], 32);
;     asm volatile("" : "+v"(q[0]), "+v"(q[1]), "+v"(q[2]), "+v"(q[3]), "+v"(q[4]), "+v"(q[5]), "+v"(q[6]), "+v"(q[7]));
; #pragma unroll
;     for (int k = 0; k < 8; ++k) rs[k >> 2][k & 3] = __builtin_amdgcn_rsqf((p[k] + q[k]) * (1.0f / 1024.0f) + RMS_EPS);
; }
;     __device__ __forceinline__ void operator()(f32x4 (&acc)[2][2][4][2], const Unit& u, int wr, int wc, int fr, int fq) const {
;     ...
;         for (int ai = 0; ai < 2; ++ai)
; #pragma unroll
;             for (int m = 0; m < 4; ++m) {
;                 const int r = row0 + ai * HALF + m * 16; const float rstd = rs[ai][m]; f32x4 a[2];
; #pragma unroll
;                 for (int n = 0; n < 2; ++n) { const f32x4 g = acc[ai][0][m][n] * rstd, uu = acc[ai][1][m][n] * rstd;
; #pragma unroll
;                     for (int i = 0; i < 4; ++i) a[n][i] = g[i] * __builtin_amdgcn_rcpf(1.0f + __builtin_amdgcn_exp2f(g[i] * -1.4426950408889634f)) * uu[i]; }
;                 *(u32x4*)(act + (size_t)r * 2816 + col0) = pack8(a[0], a[1]);
.LBB0_986:
	v_lshl_add_u32 v158, s69, 8, v161
	v_mov_b32_e32 v159, v6
	v_mov_b32_e32 v160, v7
	v_mov_b32_e32 v162, v8
	v_mov_b32_e32 v164, v9
	v_mov_b32_e32 v166, v10
	v_mov_b32_e32 v170, v11
	v_mov_b32_e32 v171, v12
	v_mov_b32_e32 v168, v13
	v_lshl_or_b32 v174, s68, 7, v165
	s_movk_i32 s47, 0x1600
	s_cmp_lg_u64 s[40:41], 0
	s_cbranch_scc0 .Lmy_pss_skip
	v_lshl_add_u32 v4, s52, 8, v161
	v_ashrrev_i32_e32 v5, 31, v4
	v_lshl_add_u64 v[4:5], v[4:5], 2, v[152:153]
	global_load_dword v6, v[4:5], off offset:704
	global_load_dword v7, v[4:5], off offset:640
	global_load_dword v8, v[4:5], off offset:576
	global_load_dword v9, v[4:5], off offset:512
	global_load_dword v10, v[4:5], off offset:192
	global_load_dword v11, v[4:5], off offset:128
	global_load_dword v12, v[4:5], off offset:64
	global_load_dword v13, v[4:5], off
.Lmy_pss_skip:
	s_andn2_b64 vcc, exec, s[40:41]
	ds_bpermute_b32 v169, v220, v168
	ds_bpermute_b32 v172, v220, v171
	ds_bpermute_b32 v173, v220, v170
	ds_bpermute_b32 v175, v220, v166
	ds_bpermute_b32 v176, v220, v164
	ds_bpermute_b32 v177, v220, v162
	ds_bpermute_b32 v178, v220, v160
	ds_bpermute_b32 v179, v220, v159
	s_waitcnt lgkmcnt(0)
	s_nop 0
	v_add_f32_e32 v168, v168, v169
	v_add_f32_e32 v169, v171, v172
	v_add_f32_e32 v170, v170, v173
	v_add_f32_e32 v166, v166, v175
	v_add_f32_e32 v164, v164, v176
	v_add_f32_e32 v162, v162, v177
	v_add_f32_e32 v160, v160, v178
	v_add_f32_e32 v159, v159, v179
	ds_bpermute_b32 v171, v221, v168
	ds_bpermute_b32 v172, v221, v169
	ds_bpermute_b32 v173, v221, v170
	ds_bpermute_b32 v175, v221, v166
	ds_bpermute_b32 v177, v221, v164
	ds_bpermute_b32 v178, v221, v162
	ds_bpermute_b32 v179, v221, v160
	ds_bpermute_b32 v182, v221, v159
	s_waitcnt lgkmcnt(0)
	s_nop 0
	v_add_f32_e32 v168, v168, v171
	v_fmamk_f32 v168, v168, 0x3a800000, v214
	v_rsq_f32_e32 v176, v168
	v_add_f32_e32 v168, v169, v172
	v_fmamk_f32 v168, v168, 0x3a800000, v214
	v_rsq_f32_e32 v172, v168
	v_add_f32_e32 v168, v170, v173
	v_add_f32_e32 v166, v166, v175
	v_add_f32_e32 v164, v164, v177
	v_add_f32_e32 v162, v162, v178
	v_add_f32_e32 v160, v160, v179
	v_add_f32_e32 v159, v159, v182
	v_fmamk_f32 v168, v168, 0x3a800000, v214
	v_fmamk_f32 v166, v166, 0x3a800000, v214
	v_fmamk_f32 v164, v164, 0x3a800000, v214
	v_fmamk_f32 v162, v162, 0x3a800000, v214
	v_fmamk_f32 v160, v160, 0x3a800000, v214
	v_fmamk_f32 v159, v159, 0x3a800000, v214
	v_pk_mul_f32 v[142:143], v[142:143], v[176:177] op_sel_hi:[1,0]
	v_rsq_f32_e32 v170, v168
	v_rsq_f32_e32 v168, v166
	v_rsq_f32_e32 v166, v164
	v_rsq_f32_e32 v164, v162
	v_rsq_f32_e32 v162, v160
	v_rsq_f32_e32 v160, v159
	v_mul_f32_e32 v159, 0xbfb8aa3b, v142
	v_exp_f32_e32 v159, v159
	v_pk_mul_f32 v[134:135], v[134:135], v[176:177] op_sel_hi:[1,0]
	v_pk_mul_f32 v[136:137], v[136:137], v[176:177] op_sel_hi:[1,0]
	v_pk_mul_f32 v[138:139], v[138:139], v[176:177] op_sel_hi:[1,0]
	v_add_f32_e32 v159, 1.0, v159
	v_rcp_f32_e32 v178, v159
	v_mul_f32_e32 v159, 0xbfb8aa3b, v143
	v_exp_f32_e32 v159, v159
	v_pk_mul_f32 v[130:131], v[130:131], v[176:177] op_sel_hi:[1,0]
	v_pk_mul_f32 v[132:133], v[132:133], v[176:177] op_sel_hi:[1,0]
	v_ashrrev_i32_e32 v175, 31, v174
	v_add_f32_e32 v159, 1.0, v159
	v_rcp_f32_e32 v179, v159
	v_pk_mul_f32 v[126:127], v[126:127], v[172:173] op_sel_hi:[1,0]
	v_pk_mul_f32 v[122:123], v[122:123], v[172:173] op_sel_hi:[1,0]
	v_pk_mul_f32 v[124:125], v[124:125], v[172:173] op_sel_hi:[1,0]
	v_pk_mul_f32 v[142:143], v[142:143], v[178:179]
	v_pk_mul_f32 v[118:119], v[118:119], v[172:173] op_sel_hi:[1,0]
	v_pk_mul_f32 v[134:135], v[134:135], v[142:143]
	v_pk_mul_f32 v[142:143], v[144:145], v[176:177] op_sel_hi:[1,0]
	v_pk_mul_f32 v[114:115], v[114:115], v[172:173] op_sel_hi:[1,0]
	v_mul_f32_e32 v144, 0xbfb8aa3b, v142
	v_mul_f32_e32 v145, 0xbfb8aa3b, v143
	v_exp_f32_e32 v144, v144
	v_exp_f32_e32 v145, v145
	v_pk_mul_f32 v[116:117], v[116:117], v[172:173] op_sel_hi:[1,0]
	v_pk_mul_f32 v[110:111], v[110:111], v[170:171] op_sel_hi:[1,0]
	v_add_f32_e32 v144, 1.0, v144
	v_add_f32_e32 v145, 1.0, v145
	v_rcp_f32_e32 v144, v144
	v_rcp_f32_e32 v145, v145
	v_pk_mul_f32 v[106:107], v[106:107], v[170:171] op_sel_hi:[1,0]
	v_pk_mul_f32 v[108:109], v[108:109], v[170:171] op_sel_hi:[1,0]
	v_pk_mul_f32 v[102:103], v[102:103], v[170:171] op_sel_hi:[1,0]
	v_pk_mul_f32 v[142:143], v[142:143], v[144:145]
	v_pk_mul_f32 v[98:99], v[98:99], v[170:171] op_sel_hi:[1,0]
	v_pk_mul_f32 v[136:137], v[136:137], v[142:143]
	v_mul_f32_e32 v142, 0xbfb8aa3b, v138
	v_mul_f32_e32 v143, 0xbfb8aa3b, v139
	v_exp_f32_e32 v142, v142
	v_exp_f32_e32 v143, v143
	v_pk_mul_f32 v[100:101], v[100:101], v[170:171] op_sel_hi:[1,0]
	v_pk_mul_f32 v[94:95], v[94:95], v[168:169] op_sel_hi:[1,0]
	v_add_f32_e32 v142, 1.0, v142
	v_add_f32_e32 v143, 1.0, v143
	v_rcp_f32_e32 v142, v142
	v_rcp_f32_e32 v143, v143
	v_pk_mul_f32 v[90:91], v[90:91], v[168:169] op_sel_hi:[1,0]
	v_pk_mul_f32 v[92:93], v[92:93], v[168:169] op_sel_hi:[1,0]
	v_pk_mul_f32 v[86:87], v[86:87], v[168:169] op_sel_hi:[1,0]
	v_pk_mul_f32 v[138:139], v[138:139], v[142:143]
	v_pk_mul_f32 v[82:83], v[82:83], v[168:169] op_sel_hi:[1,0]
	v_pk_mul_f32 v[138:139], v[130:131], v[138:139]
	v_pk_mul_f32 v[130:131], v[140:141], v[176:177] op_sel_hi:[1,0]
	v_pk_mul_f32 v[84:85], v[84:85], v[168:169] op_sel_hi:[1,0]
	v_mul_f32_e32 v140, 0xbfb8aa3b, v130
	v_mul_f32_e32 v141, 0xbfb8aa3b, v131
	v_exp_f32_e32 v140, v140
	v_exp_f32_e32 v141, v141
	v_pk_mul_f32 v[78:79], v[78:79], v[166:167] op_sel_hi:[1,0]
	v_pk_mul_f32 v[74:75], v[74:75], v[166:167] op_sel_hi:[1,0]
	v_add_f32_e32 v140, 1.0, v140
	v_add_f32_e32 v141, 1.0, v141
	v_rcp_f32_e32 v140, v140
	v_rcp_f32_e32 v141, v141
; __device__ __forceinline__ u32x4 pack8(const f32x4 a, const f32x4 b) { u32x4 w; w.x = cvt_pk_bf16(a[0], a[1]); w.y = cvt_pk_bf16(a[2], a[3]); w.z = cvt_pk_bf16(b[0], b[1]); w.w = cvt_pk_bf16(b[2], b[3]); return w; }
;     __device__ __forceinline__ void operator()(f32x4 (&acc)[2][2][4][2], const Unit& u, int wr, int wc, int fr, int fq) const {
;     ...
;         for (int ai = 0; ai < 2; ++ai)
; #pragma unroll
;             for (int m = 0; m < 4; ++m) {
;                 const int r = row0 + ai * HALF + m * 16; const float rstd = rs[ai][m]; f32x4 a[2];
; #pragma unroll
;                 for (int n = 0; n < 2; ++n) { const f32x4 g = acc[ai][0][m][n] * rstd, uu = acc[ai][1][m][n] * rstd;
; #pragma unroll
;                     for (int i = 0; i < 4; ++i) a[n][i] = g[i] * __builtin_amdgcn_rcpf(1.0f + __builtin_amdgcn_exp2f(g[i] * -1.4426950408889634f)) * uu[i]; }
;                 *(u32x4*)(act + (size_t)r * 2816 + col0) = pack8(a[0], a[1]);
	v_pk_mul_f32 v[76:77], v[76:77], v[166:167] op_sel_hi:[1,0]
	v_pk_mul_f32 v[70:71], v[70:71], v[166:167] op_sel_hi:[1,0]
	v_pk_mul_f32 v[66:67], v[66:67], v[166:167] op_sel_hi:[1,0]
	v_pk_mul_f32 v[130:131], v[130:131], v[140:141]
	v_pk_mul_f32 v[68:69], v[68:69], v[166:167] op_sel_hi:[1,0]
	v_pk_mul_f32 v[140:141], v[132:133], v[130:131]
	v_cvt_pk_bf16_f32 v130, v134, v135
	v_mov_b64_e32 v[134:135], s[42:43]
	v_cvt_pk_bf16_f32 v131, v136, v137
	v_cvt_pk_bf16_f32 v132, v138, v139
	v_mad_i64_i32 v[138:139], s[58:59], v158, s47, v[134:135]
	v_lshlrev_b64 v[136:137], 1, v[174:175]
	v_cvt_pk_bf16_f32 v133, v140, v141
	v_lshl_add_u64 v[138:139], v[138:139], 0, v[136:137]
	global_store_dwordx4 v[138:139], v[130:133], off
	v_pk_mul_f32 v[62:63], v[62:63], v[164:165] op_sel_hi:[1,0]
	v_pk_mul_f32 v[58:59], v[58:59], v[164:165] op_sel_hi:[1,0]
	v_mul_f32_e32 v130, 0xbfb8aa3b, v126
	v_mul_f32_e32 v131, 0xbfb8aa3b, v127
	v_exp_f32_e32 v130, v130
	v_exp_f32_e32 v131, v131
	v_pk_mul_f32 v[60:61], v[60:61], v[164:165] op_sel_hi:[1,0]
	v_pk_mul_f32 v[54:55], v[54:55], v[164:165] op_sel_hi:[1,0]
	v_add_f32_e32 v130, 1.0, v130
	v_add_f32_e32 v131, 1.0, v131
	v_rcp_f32_e32 v130, v130
	v_rcp_f32_e32 v131, v131
	v_pk_mul_f32 v[50:51], v[50:51], v[164:165] op_sel_hi:[1,0]
	v_pk_mul_f32 v[52:53], v[52:53], v[164:165] op_sel_hi:[1,0]
	v_pk_mul_f32 v[46:47], v[46:47], v[162:163] op_sel_hi:[1,0]
	v_pk_mul_f32 v[126:127], v[126:127], v[130:131]
	v_pk_mul_f32 v[42:43], v[42:43], v[162:163] op_sel_hi:[1,0]
	v_pk_mul_f32 v[122:123], v[122:123], v[126:127]
	v_pk_mul_f32 v[126:127], v[128:129], v[172:173] op_sel_hi:[1,0]
	v_pk_mul_f32 v[44:45], v[44:45], v[162:163] op_sel_hi:[1,0]
	v_mul_f32_e32 v128, 0xbfb8aa3b, v126
	v_mul_f32_e32 v129, 0xbfb8aa3b, v127
	v_exp_f32_e32 v128, v128
	v_exp_f32_e32 v129, v129
	v_pk_mul_f32 v[38:39], v[38:39], v[162:163] op_sel_hi:[1,0]
	v_pk_mul_f32 v[34:35], v[34:35], v[162:163] op_sel_hi:[1,0]
	v_add_f32_e32 v128, 1.0, v128
	v_add_f32_e32 v129, 1.0, v129
	v_rcp_f32_e32 v128, v128
	v_rcp_f32_e32 v129, v129
	v_pk_mul_f32 v[36:37], v[36:37], v[162:163] op_sel_hi:[1,0]
	v_pk_mul_f32 v[30:31], v[30:31], v[160:161] op_sel_hi:[1,0]
	v_pk_mul_f32 v[26:27], v[26:27], v[160:161] op_sel_hi:[1,0]
	v_pk_mul_f32 v[126:127], v[126:127], v[128:129]
	v_pk_mul_f32 v[28:29], v[28:29], v[160:161] op_sel_hi:[1,0]
	v_pk_mul_f32 v[124:125], v[124:125], v[126:127]
	v_mul_f32_e32 v126, 0xbfb8aa3b, v118
	v_mul_f32_e32 v127, 0xbfb8aa3b, v119
	v_exp_f32_e32 v126, v126
	v_exp_f32_e32 v127, v127
	v_pk_mul_f32 v[22:23], v[22:23], v[160:161] op_sel_hi:[1,0]
	v_pk_mul_f32 v[18:19], v[18:19], v[160:161] op_sel_hi:[1,0]
	v_add_f32_e32 v126, 1.0, v126
	v_add_f32_e32 v127, 1.0, v127
	v_rcp_f32_e32 v126, v126
	v_rcp_f32_e32 v127, v127
	v_pk_mul_f32 v[20:21], v[20:21], v[160:161] op_sel_hi:[1,0]
	v_pk_mul_f32 v[118:119], v[118:119], v[126:127]
	s_nop 0
	v_pk_mul_f32 v[118:119], v[114:115], v[118:119]
	v_pk_mul_f32 v[114:115], v[120:121], v[172:173] op_sel_hi:[1,0]
	v_or_b32_e32 v126, 16, v158
	v_mul_f32_e32 v120, 0xbfb8aa3b, v114
	v_mul_f32_e32 v121, 0xbfb8aa3b, v115
	v_exp_f32_e32 v120, v120
	v_exp_f32_e32 v121, v121
	v_add_f32_e32 v120, 1.0, v120
	v_add_f32_e32 v121, 1.0, v121
	v_rcp_f32_e32 v120, v120
	v_rcp_f32_e32 v121, v121
	s_nop 0
	v_pk_mul_f32 v[114:115], v[114:115], v[120:121]
	s_nop 0
	v_pk_mul_f32 v[120:121], v[116:117], v[114:115]
	v_cvt_pk_bf16_f32 v116, v118, v119
	v_mad_i64_i32 v[118:119], s[58:59], v126, s47, v[134:135]
	v_cvt_pk_bf16_f32 v114, v122, v123
	v_cvt_pk_bf16_f32 v115, v124, v125
	v_cvt_pk_bf16_f32 v117, v120, v121
	v_lshl_add_u64 v[118:119], v[118:119], 0, v[136:137]
	global_store_dwordx4 v[118:119], v[114:117], off
	s_nop 1
	v_mul_f32_e32 v114, 0xbfb8aa3b, v110
	v_mul_f32_e32 v115, 0xbfb8aa3b, v111
	v_exp_f32_e32 v114, v114
	v_exp_f32_e32 v115, v115
	v_add_f32_e32 v114, 1.0, v114
	v_add_f32_e32 v115, 1.0, v115
	v_rcp_f32_e32 v114, v114
	v_rcp_f32_e32 v115, v115
	s_nop 0
	v_pk_mul_f32 v[110:111], v[110:111], v[114:115]
	s_nop 0
	v_pk_mul_f32 v[106:107], v[106:107], v[110:111]
	v_pk_mul_f32 v[110:111], v[112:113], v[170:171] op_sel_hi:[1,0]
	s_nop 0
	v_mul_f32_e32 v112, 0xbfb8aa3b, v110
	v_mul_f32_e32 v113, 0xbfb8aa3b, v111
	v_exp_f32_e32 v112, v112
	v_exp_f32_e32 v113, v113
	v_add_f32_e32 v112, 1.0, v112
	v_add_f32_e32 v113, 1.0, v113
	v_rcp_f32_e32 v112, v112
	v_rcp_f32_e32 v113, v113
	s_nop 0
	v_pk_mul_f32 v[110:111], v[110:111], v[112:113]
	s_nop 0
	v_pk_mul_f32 v[108:109], v[108:109], v[110:111]
	v_mul_f32_e32 v110, 0xbfb8aa3b, v102
	v_mul_f32_e32 v111, 0xbfb8aa3b, v103
	v_exp_f32_e32 v110, v110
	v_exp_f32_e32 v111, v111
	v_add_f32_e32 v110, 1.0, v110
	v_add_f32_e32 v111, 1.0, v111
	v_rcp_f32_e32 v110, v110
	v_rcp_f32_e32 v111, v111
	s_nop 0
	v_pk_mul_f32 v[102:103], v[102:103], v[110:111]
	s_nop 0
	v_pk_mul_f32 v[102:103], v[98:99], v[102:103]
	v_pk_mul_f32 v[98:99], v[104:105], v[170:171] op_sel_hi:[1,0]
	v_or_b32_e32 v110, 32, v158
	v_mul_f32_e32 v104, 0xbfb8aa3b, v98
	v_mul_f32_e32 v105, 0xbfb8aa3b, v99
	v_exp_f32_e32 v104, v104
	v_exp_f32_e32 v105, v105
	v_add_f32_e32 v104, 1.0, v104
	v_add_f32_e32 v105, 1.0, v105
	v_rcp_f32_e32 v104, v104
	v_rcp_f32_e32 v105, v105
	s_nop 0
	v_pk_mul_f32 v[98:99], v[98:99], v[104:105]
	s_nop 0
	v_pk_mul_f32 v[104:105], v[100:101], v[98:99]
	v_cvt_pk_bf16_f32 v100, v102, v103
	v_mad_i64_i32 v[102:103], s[58:59], v110, s47, v[134:135]
	v_cvt_pk_bf16_f32 v98, v106, v107
	v_cvt_pk_bf16_f32 v99, v108, v109
	v_cvt_pk_bf16_f32 v101, v104, v105
	v_lshl_add_u64 v[102:103], v[102:103], 0, v[136:137]
	global_store_dwordx4 v[102:103], v[98:101], off
	s_nop 1
	v_mul_f32_e32 v98, 0xbfb8aa3b, v94
; __device__ __forceinline__ u32x4 pack8(const f32x4 a, const f32x4 b) { u32x4 w; w.x = cvt_pk_bf16(a[0], a[1]); w.y = cvt_pk_bf16(a[2], a[3]); w.z = cvt_pk_bf16(b[0], b[1]); w.w = cvt_pk_bf16(b[2], b[3]); return w; }
;     __device__ __forceinline__ void operator()(f32x4 (&acc)[2][2][4][2], const Unit& u, int wr, int wc, int fr, int fq) const {
;     ...
;         for (int ai = 0; ai < 2; ++ai)
; #pragma unroll
;             for (int m = 0; m < 4; ++m) {
;                 const int r = row0 + ai * HALF + m * 16; const float rstd = rs[ai][m]; f32x4 a[2];
; #pragma unroll
;                 for (int n = 0; n < 2; ++n) { const f32x4 g = acc[ai][0][m][n] * rstd, uu = acc[ai][1][m][n] * rstd;
; #pragma unroll
;                     for (int i = 0; i < 4; ++i) a[n][i] = g[i] * __builtin_amdgcn_rcpf(1.0f + __builtin_amdgcn_exp2f(g[i] * -1.4426950408889634f)) * uu[i]; }
;                 *(u32x4*)(act + (size_t)r * 2816 + col0) = pack8(a[0], a[1]);
	v_mul_f32_e32 v99, 0xbfb8aa3b, v95
	v_exp_f32_e32 v98, v98
	v_exp_f32_e32 v99, v99
	v_add_f32_e32 v98, 1.0, v98
	v_add_f32_e32 v99, 1.0, v99
	v_rcp_f32_e32 v98, v98
	v_rcp_f32_e32 v99, v99
	s_nop 0
	v_pk_mul_f32 v[94:95], v[94:95], v[98:99]
	s_nop 0
	v_pk_mul_f32 v[90:91], v[90:91], v[94:95]
	v_pk_mul_f32 v[94:95], v[96:97], v[168:169] op_sel_hi:[1,0]
	s_nop 0
	v_mul_f32_e32 v96, 0xbfb8aa3b, v94
	v_mul_f32_e32 v97, 0xbfb8aa3b, v95
	v_exp_f32_e32 v96, v96
	v_exp_f32_e32 v97, v97
	v_add_f32_e32 v96, 1.0, v96
	v_add_f32_e32 v97, 1.0, v97
	v_rcp_f32_e32 v96, v96
	v_rcp_f32_e32 v97, v97
	s_nop 0
	v_pk_mul_f32 v[94:95], v[94:95], v[96:97]
	s_nop 0
	v_pk_mul_f32 v[92:93], v[92:93], v[94:95]
	v_mul_f32_e32 v94, 0xbfb8aa3b, v86
	v_mul_f32_e32 v95, 0xbfb8aa3b, v87
	v_exp_f32_e32 v94, v94
	v_exp_f32_e32 v95, v95
	v_add_f32_e32 v94, 1.0, v94
	v_add_f32_e32 v95, 1.0, v95
	v_rcp_f32_e32 v94, v94
	v_rcp_f32_e32 v95, v95
	s_nop 0
	v_pk_mul_f32 v[86:87], v[86:87], v[94:95]
	s_nop 0
	v_pk_mul_f32 v[86:87], v[82:83], v[86:87]
	v_pk_mul_f32 v[82:83], v[88:89], v[168:169] op_sel_hi:[1,0]
	v_or_b32_e32 v94, 48, v158
	v_mul_f32_e32 v88, 0xbfb8aa3b, v82
	v_mul_f32_e32 v89, 0xbfb8aa3b, v83
	v_exp_f32_e32 v88, v88
	v_exp_f32_e32 v89, v89
	v_add_f32_e32 v88, 1.0, v88
	v_add_f32_e32 v89, 1.0, v89
	v_rcp_f32_e32 v88, v88
	v_rcp_f32_e32 v89, v89
	s_nop 0
	v_pk_mul_f32 v[82:83], v[82:83], v[88:89]
	s_nop 0
	v_pk_mul_f32 v[88:89], v[84:85], v[82:83]
	v_cvt_pk_bf16_f32 v84, v86, v87
	v_mad_i64_i32 v[86:87], s[58:59], v94, s47, v[134:135]
	v_cvt_pk_bf16_f32 v82, v90, v91
	v_cvt_pk_bf16_f32 v83, v92, v93
	v_cvt_pk_bf16_f32 v85, v88, v89
	v_lshl_add_u64 v[86:87], v[86:87], 0, v[136:137]
	global_store_dwordx4 v[86:87], v[82:85], off
	s_nop 1
	v_mul_f32_e32 v82, 0xbfb8aa3b, v78
	v_mul_f32_e32 v83, 0xbfb8aa3b, v79
	v_exp_f32_e32 v82, v82
	v_exp_f32_e32 v83, v83
	v_add_u32_e32 v84, 0x80, v158
	v_add_f32_e32 v82, 1.0, v82
	v_add_f32_e32 v83, 1.0, v83
	v_rcp_f32_e32 v82, v82
	v_rcp_f32_e32 v83, v83
	s_nop 0
	v_pk_mul_f32 v[78:79], v[78:79], v[82:83]
	s_nop 0
	v_pk_mul_f32 v[74:75], v[74:75], v[78:79]
	v_pk_mul_f32 v[78:79], v[80:81], v[166:167] op_sel_hi:[1,0]
	s_nop 0
	v_mul_f32_e32 v80, 0xbfb8aa3b, v78
	v_mul_f32_e32 v81, 0xbfb8aa3b, v79
	v_exp_f32_e32 v80, v80
	v_exp_f32_e32 v81, v81
	v_add_f32_e32 v80, 1.0, v80
	v_add_f32_e32 v81, 1.0, v81
	v_rcp_f32_e32 v80, v80
	v_rcp_f32_e32 v81, v81
	s_nop 0
	v_pk_mul_f32 v[78:79], v[78:79], v[80:81]
	s_nop 0
	v_pk_mul_f32 v[76:77], v[76:77], v[78:79]
	v_mul_f32_e32 v78, 0xbfb8aa3b, v70
	v_mul_f32_e32 v79, 0xbfb8aa3b, v71
	v_exp_f32_e32 v78, v78
	v_exp_f32_e32 v79, v79
	v_add_f32_e32 v78, 1.0, v78
	v_add_f32_e32 v79, 1.0, v79
	v_rcp_f32_e32 v78, v78
	v_rcp_f32_e32 v79, v79
	s_nop 0
	v_pk_mul_f32 v[70:71], v[70:71], v[78:79]
	s_nop 0
	v_pk_mul_f32 v[70:71], v[66:67], v[70:71]
	v_pk_mul_f32 v[66:67], v[72:73], v[166:167] op_sel_hi:[1,0]
	s_nop 0
	v_mul_f32_e32 v72, 0xbfb8aa3b, v66
	v_mul_f32_e32 v73, 0xbfb8aa3b, v67
	v_exp_f32_e32 v72, v72
	v_exp_f32_e32 v73, v73
	v_add_f32_e32 v72, 1.0, v72
	v_add_f32_e32 v73, 1.0, v73
	v_rcp_f32_e32 v72, v72
	v_rcp_f32_e32 v73, v73
	s_nop 0
	v_pk_mul_f32 v[66:67], v[66:67], v[72:73]
	s_nop 0
	v_pk_mul_f32 v[72:73], v[68:69], v[66:67]
	v_cvt_pk_bf16_f32 v68, v70, v71
	v_mad_i64_i32 v[70:71], s[58:59], v84, s47, v[134:135]
	v_cvt_pk_bf16_f32 v66, v74, v75
	v_cvt_pk_bf16_f32 v67, v76, v77
	v_cvt_pk_bf16_f32 v69, v72, v73
	v_lshl_add_u64 v[70:71], v[70:71], 0, v[136:137]
	global_store_dwordx4 v[70:71], v[66:69], off
	s_nop 1
	v_mul_f32_e32 v66, 0xbfb8aa3b, v62
	v_mul_f32_e32 v67, 0xbfb8aa3b, v63
	v_exp_f32_e32 v66, v66
	v_exp_f32_e32 v67, v67
	v_add_f32_e32 v66, 1.0, v66
	v_add_f32_e32 v67, 1.0, v67
	v_rcp_f32_e32 v66, v66
	v_rcp_f32_e32 v67, v67
	s_nop 0
	v_pk_mul_f32 v[62:63], v[62:63], v[66:67]
	s_nop 0
	v_pk_mul_f32 v[58:59], v[58:59], v[62:63]
	v_pk_mul_f32 v[62:63], v[64:65], v[164:165] op_sel_hi:[1,0]
	s_nop 0
	v_mul_f32_e32 v64, 0xbfb8aa3b, v62
	v_mul_f32_e32 v65, 0xbfb8aa3b, v63
	v_exp_f32_e32 v64, v64
	v_exp_f32_e32 v65, v65
	v_add_f32_e32 v64, 1.0, v64
	v_add_f32_e32 v65, 1.0, v65
	v_rcp_f32_e32 v64, v64
	v_rcp_f32_e32 v65, v65
	s_nop 0
	v_pk_mul_f32 v[62:63], v[62:63], v[64:65]
	s_nop 0
	v_pk_mul_f32 v[60:61], v[60:61], v[62:63]
	v_mul_f32_e32 v62, 0xbfb8aa3b, v54
	v_mul_f32_e32 v63, 0xbfb8aa3b, v55
	v_exp_f32_e32 v62, v62
	v_exp_f32_e32 v63, v63
	v_add_f32_e32 v62, 1.0, v62
	v_add_f32_e32 v63, 1.0, v63
	v_rcp_f32_e32 v62, v62
	v_rcp_f32_e32 v63, v63
	s_nop 0
; __device__ __forceinline__ u32x4 pack8(const f32x4 a, const f32x4 b) { u32x4 w; w.x = cvt_pk_bf16(a[0], a[1]); w.y = cvt_pk_bf16(a[2], a[3]); w.z = cvt_pk_bf16(b[0], b[1]); w.w = cvt_pk_bf16(b[2], b[3]); return w; }
;     __device__ __forceinline__ void operator()(f32x4 (&acc)[2][2][4][2], const Unit& u, int wr, int wc, int fr, int fq) const {
;     ...
;         for (int ai = 0; ai < 2; ++ai)
; #pragma unroll
;             for (int m = 0; m < 4; ++m) {
;                 const int r = row0 + ai * HALF + m * 16; const float rstd = rs[ai][m]; f32x4 a[2];
; #pragma unroll
;                 for (int n = 0; n < 2; ++n) { const f32x4 g = acc[ai][0][m][n] * rstd, uu = acc[ai][1][m][n] * rstd;
; #pragma unroll
;                     for (int i = 0; i < 4; ++i) a[n][i] = g[i] * __builtin_amdgcn_rcpf(1.0f + __builtin_amdgcn_exp2f(g[i] * -1.4426950408889634f)) * uu[i]; }
;                 *(u32x4*)(act + (size_t)r * 2816 + col0) = pack8(a[0], a[1]);
	v_pk_mul_f32 v[54:55], v[54:55], v[62:63]
	s_nop 0
	v_pk_mul_f32 v[54:55], v[50:51], v[54:55]
	v_pk_mul_f32 v[50:51], v[56:57], v[164:165] op_sel_hi:[1,0]
	v_add_u32_e32 v62, 0x90, v158
	v_mul_f32_e32 v56, 0xbfb8aa3b, v50
	v_mul_f32_e32 v57, 0xbfb8aa3b, v51
	v_exp_f32_e32 v56, v56
	v_exp_f32_e32 v57, v57
	v_add_f32_e32 v56, 1.0, v56
	v_add_f32_e32 v57, 1.0, v57
	v_rcp_f32_e32 v56, v56
	v_rcp_f32_e32 v57, v57
	s_nop 0
	v_pk_mul_f32 v[50:51], v[50:51], v[56:57]
	s_nop 0
	v_pk_mul_f32 v[56:57], v[52:53], v[50:51]
	v_cvt_pk_bf16_f32 v52, v54, v55
	v_mad_i64_i32 v[54:55], s[58:59], v62, s47, v[134:135]
	v_cvt_pk_bf16_f32 v50, v58, v59
	v_cvt_pk_bf16_f32 v51, v60, v61
	v_cvt_pk_bf16_f32 v53, v56, v57
	v_lshl_add_u64 v[54:55], v[54:55], 0, v[136:137]
	global_store_dwordx4 v[54:55], v[50:53], off
	s_nop 1
	v_mul_f32_e32 v50, 0xbfb8aa3b, v46
	v_mul_f32_e32 v51, 0xbfb8aa3b, v47
	v_exp_f32_e32 v50, v50
	v_exp_f32_e32 v51, v51
	v_add_f32_e32 v50, 1.0, v50
	v_add_f32_e32 v51, 1.0, v51
	v_rcp_f32_e32 v50, v50
	v_rcp_f32_e32 v51, v51
	s_nop 0
	v_pk_mul_f32 v[46:47], v[46:47], v[50:51]
	s_nop 0
	v_pk_mul_f32 v[42:43], v[42:43], v[46:47]
	v_pk_mul_f32 v[46:47], v[48:49], v[162:163] op_sel_hi:[1,0]
	s_nop 0
	v_mul_f32_e32 v48, 0xbfb8aa3b, v46
	v_mul_f32_e32 v49, 0xbfb8aa3b, v47
	v_exp_f32_e32 v48, v48
	v_exp_f32_e32 v49, v49
	v_add_f32_e32 v48, 1.0, v48
	v_add_f32_e32 v49, 1.0, v49
	v_rcp_f32_e32 v48, v48
	v_rcp_f32_e32 v49, v49
	s_nop 0
	v_pk_mul_f32 v[46:47], v[46:47], v[48:49]
	s_nop 0
	v_pk_mul_f32 v[44:45], v[44:45], v[46:47]
	v_mul_f32_e32 v46, 0xbfb8aa3b, v38
	v_mul_f32_e32 v47, 0xbfb8aa3b, v39
	v_exp_f32_e32 v46, v46
	v_exp_f32_e32 v47, v47
	v_add_f32_e32 v46, 1.0, v46
	v_add_f32_e32 v47, 1.0, v47
	v_rcp_f32_e32 v46, v46
	v_rcp_f32_e32 v47, v47
	s_nop 0
	v_pk_mul_f32 v[38:39], v[38:39], v[46:47]
	s_nop 0
	v_pk_mul_f32 v[38:39], v[34:35], v[38:39]
	v_pk_mul_f32 v[34:35], v[40:41], v[162:163] op_sel_hi:[1,0]
	v_add_u32_e32 v46, 0xa0, v158
	v_mul_f32_e32 v40, 0xbfb8aa3b, v34
	v_mul_f32_e32 v41, 0xbfb8aa3b, v35
	v_exp_f32_e32 v40, v40
	v_exp_f32_e32 v41, v41
	v_add_f32_e32 v40, 1.0, v40
	v_add_f32_e32 v41, 1.0, v41
	v_rcp_f32_e32 v40, v40
	v_rcp_f32_e32 v41, v41
	s_nop 0
	v_pk_mul_f32 v[34:35], v[34:35], v[40:41]
	s_nop 0
	v_pk_mul_f32 v[40:41], v[36:37], v[34:35]
	v_cvt_pk_bf16_f32 v36, v38, v39
	v_mad_i64_i32 v[38:39], s[58:59], v46, s47, v[134:135]
	v_cvt_pk_bf16_f32 v34, v42, v43
	v_cvt_pk_bf16_f32 v35, v44, v45
	v_cvt_pk_bf16_f32 v37, v40, v41
	v_lshl_add_u64 v[38:39], v[38:39], 0, v[136:137]
	global_store_dwordx4 v[38:39], v[34:37], off
	s_nop 1
	v_mul_f32_e32 v34, 0xbfb8aa3b, v30
	v_mul_f32_e32 v35, 0xbfb8aa3b, v31
	v_exp_f32_e32 v34, v34
	v_exp_f32_e32 v35, v35
	v_add_f32_e32 v34, 1.0, v34
	v_add_f32_e32 v35, 1.0, v35
	v_rcp_f32_e32 v34, v34
	v_rcp_f32_e32 v35, v35
	s_nop 0
	v_pk_mul_f32 v[30:31], v[30:31], v[34:35]
	s_nop 0
	v_pk_mul_f32 v[26:27], v[26:27], v[30:31]
	v_pk_mul_f32 v[30:31], v[32:33], v[160:161] op_sel_hi:[1,0]
	s_nop 0
	v_mul_f32_e32 v32, 0xbfb8aa3b, v30
	v_mul_f32_e32 v33, 0xbfb8aa3b, v31
	v_exp_f32_e32 v32, v32
	v_exp_f32_e32 v33, v33
	v_add_f32_e32 v32, 1.0, v32
	v_add_f32_e32 v33, 1.0, v33
	v_rcp_f32_e32 v32, v32
	v_rcp_f32_e32 v33, v33
	s_nop 0
	v_pk_mul_f32 v[30:31], v[30:31], v[32:33]
	s_nop 0
	v_pk_mul_f32 v[28:29], v[28:29], v[30:31]
	v_mul_f32_e32 v30, 0xbfb8aa3b, v22
	v_mul_f32_e32 v31, 0xbfb8aa3b, v23
	v_exp_f32_e32 v30, v30
	v_exp_f32_e32 v31, v31
	v_add_f32_e32 v30, 1.0, v30
	v_add_f32_e32 v31, 1.0, v31
	v_rcp_f32_e32 v30, v30
	v_rcp_f32_e32 v31, v31
	s_nop 0
	v_pk_mul_f32 v[22:23], v[22:23], v[30:31]
	s_nop 0
	v_pk_mul_f32 v[22:23], v[18:19], v[22:23]
	v_pk_mul_f32 v[18:19], v[24:25], v[160:161] op_sel_hi:[1,0]
	v_add_u32_e32 v30, 0xb0, v158
	v_mul_f32_e32 v24, 0xbfb8aa3b, v18
	v_mul_f32_e32 v25, 0xbfb8aa3b, v19
	v_exp_f32_e32 v24, v24
	v_exp_f32_e32 v25, v25
	v_add_f32_e32 v24, 1.0, v24
	v_add_f32_e32 v25, 1.0, v25
	v_rcp_f32_e32 v24, v24
	v_rcp_f32_e32 v25, v25
	s_nop 0
	v_pk_mul_f32 v[18:19], v[18:19], v[24:25]
	s_nop 0
	v_pk_mul_f32 v[24:25], v[20:21], v[18:19]
	v_cvt_pk_bf16_f32 v20, v22, v23
	v_mad_i64_i32 v[22:23], s[58:59], v30, s47, v[134:135]
	v_cvt_pk_bf16_f32 v18, v26, v27
	v_cvt_pk_bf16_f32 v19, v28, v29
	v_cvt_pk_bf16_f32 v21, v24, v25
	v_lshl_add_u64 v[22:23], v[22:23], 0, v[136:137]
	s_mov_b64 s[58:59], -1
	global_store_dwordx4 v[22:23], v[18:21], off
	s_waitcnt vmcnt(8)
	s_cbranch_vccnz .LBB0_979
	s_andn2_b64 vcc, exec, s[38:39]
	s_cbranch_vccnz .LBB0_978
	s_barrier
	s_branch .LBB0_978
